# v1 + adaLN GEMV row loop: 37 serialized load/wait pairs replaced by 3 batches of 12 loads with counted vmcnt
# speedup vs baseline: 1.0070x; 1.0029x over previous
; __device__ __forceinline__ void prologue(const Args& A, LAS unsigned char* lds, int vcu, int G, const int tid) {
;     ...
;             const int n0 = it * 72, c4 = tid % 18, kg = tid / 18;
;             f32x4 a0 = {0.f, 0.f, 0.f, 0.f}, a1 = a0, a2 = a0, a3 = a0, a4 = a0;
;             if (kg < 28) {
;                 const float* wp = A.in[I_WADA] + n0 + 4 * c4;
; #pragma unroll 8
;                 for (int kk = 0; kk < 37; ++kk) { const int k = kg + 28 * kk; if (k < 1024) { const f32x4 w = __builtin_nontemporal_load((const f32x4*)(wp + (size_t)k * MODLD));
;                     a0 += w * sc[k]; a1 += w * sc[1024 + k]; a2 += w * sc[2048 + k]; a3 += w * sc[3072 + k]; a4 += w * sc[4096 + k]; } }
.LBB0_155:
	s_or_b64 exec, exec, s[2:3]
	s_waitcnt lgkmcnt(0)
	s_barrier
	s_and_saveexec_b64 s[2:3], s[68:69]
	s_cbranch_execz .LBB0_177
	s_ashr_i32 s75, s74, 31
	v_lshl_add_u64 v[80:81], s[74:75], 2, v[62:63]
	v_mov_b32_e32 v49, v106
	s_mov_b32 s45, 0
	v_mov_b32_e32 v26, 0
	v_mov_b32_e32 v27, 0
	v_mov_b32_e32 v28, 0
	v_mov_b32_e32 v29, 0
	v_mov_b32_e32 v30, 0
	v_mov_b32_e32 v31, 0
	v_mov_b32_e32 v32, 0
	v_mov_b32_e32 v33, 0
	v_mov_b32_e32 v34, 0
	v_mov_b32_e32 v35, 0
	v_mov_b32_e32 v36, 0
	v_mov_b32_e32 v37, 0
	v_mov_b32_e32 v38, 0
	v_mov_b32_e32 v39, 0
	v_mov_b32_e32 v40, 0
	v_mov_b32_e32 v41, 0
	v_mov_b32_e32 v42, 0
	v_mov_b32_e32 v43, 0
	v_mov_b32_e32 v44, 0
	v_mov_b32_e32 v45, 0
	s_mov_b32 s44, 0x0
	v_lshl_add_u64 v[188:189], v[80:81], 0, s[44:45]
	global_load_dwordx4 v[128:131], v[188:189], off nt
	s_mov_b32 s44, 0xfc000
	v_lshl_add_u64 v[188:189], v[80:81], 0, s[44:45]
	global_load_dwordx4 v[132:135], v[188:189], off nt
	s_mov_b32 s44, 0x1f8000
	v_lshl_add_u64 v[188:189], v[80:81], 0, s[44:45]
	global_load_dwordx4 v[136:139], v[188:189], off nt
	s_mov_b32 s44, 0x2f4000
	v_lshl_add_u64 v[188:189], v[80:81], 0, s[44:45]
	global_load_dwordx4 v[140:143], v[188:189], off nt
	s_mov_b32 s44, 0x3f0000
	v_lshl_add_u64 v[188:189], v[80:81], 0, s[44:45]
	global_load_dwordx4 v[144:147], v[188:189], off nt
	s_mov_b32 s44, 0x4ec000
	v_lshl_add_u64 v[188:189], v[80:81], 0, s[44:45]
	global_load_dwordx4 v[148:151], v[188:189], off nt
	s_mov_b32 s44, 0x5e8000
	v_lshl_add_u64 v[188:189], v[80:81], 0, s[44:45]
	global_load_dwordx4 v[152:155], v[188:189], off nt
	s_mov_b32 s44, 0x6e4000
	v_lshl_add_u64 v[188:189], v[80:81], 0, s[44:45]
	global_load_dwordx4 v[156:159], v[188:189], off nt
	s_mov_b32 s44, 0x7e0000
	v_lshl_add_u64 v[188:189], v[80:81], 0, s[44:45]
	global_load_dwordx4 v[160:163], v[188:189], off nt
	s_mov_b32 s44, 0x8dc000
	v_lshl_add_u64 v[188:189], v[80:81], 0, s[44:45]
	global_load_dwordx4 v[164:167], v[188:189], off nt
	s_mov_b32 s44, 0x9d8000
	v_lshl_add_u64 v[188:189], v[80:81], 0, s[44:45]
	global_load_dwordx4 v[168:171], v[188:189], off nt
	s_mov_b32 s44, 0xad4000
	v_lshl_add_u64 v[188:189], v[80:81], 0, s[44:45]
	global_load_dwordx4 v[172:175], v[188:189], off nt
	ds_read_b32 v190, v49
	ds_read_b32 v192, v49 offset:4096
	ds_read_b32 v194, v49 offset:8192
	ds_read_b32 v196, v49 offset:12288
	ds_read_b32 v198, v49 offset:16384
	s_waitcnt vmcnt(11) lgkmcnt(0)
	v_pk_fma_f32 v[42:43], v[128:129], v[190:191], v[42:43] op_sel_hi:[1,0,1]
	v_pk_fma_f32 v[44:45], v[130:131], v[190:191], v[44:45] op_sel_hi:[1,0,1]
	v_pk_fma_f32 v[38:39], v[128:129], v[192:193], v[38:39] op_sel_hi:[1,0,1]
	v_pk_fma_f32 v[40:41], v[130:131], v[192:193], v[40:41] op_sel_hi:[1,0,1]
	v_pk_fma_f32 v[34:35], v[128:129], v[194:195], v[34:35] op_sel_hi:[1,0,1]
	v_pk_fma_f32 v[36:37], v[130:131], v[194:195], v[36:37] op_sel_hi:[1,0,1]
	v_pk_fma_f32 v[30:31], v[128:129], v[196:197], v[30:31] op_sel_hi:[1,0,1]
	v_pk_fma_f32 v[32:33], v[130:131], v[196:197], v[32:33] op_sel_hi:[1,0,1]
	v_pk_fma_f32 v[26:27], v[128:129], v[198:199], v[26:27] op_sel_hi:[1,0,1]
	v_pk_fma_f32 v[28:29], v[130:131], v[198:199], v[28:29] op_sel_hi:[1,0,1]
	ds_read_b32 v190, v49 offset:112
	ds_read_b32 v192, v49 offset:4208
	ds_read_b32 v194, v49 offset:8304
	ds_read_b32 v196, v49 offset:12400
	ds_read_b32 v198, v49 offset:16496
	s_waitcnt vmcnt(10) lgkmcnt(0)
	v_pk_fma_f32 v[42:43], v[132:133], v[190:191], v[42:43] op_sel_hi:[1,0,1]
	v_pk_fma_f32 v[44:45], v[134:135], v[190:191], v[44:45] op_sel_hi:[1,0,1]
	v_pk_fma_f32 v[38:39], v[132:133], v[192:193], v[38:39] op_sel_hi:[1,0,1]
	v_pk_fma_f32 v[40:41], v[134:135], v[192:193], v[40:41] op_sel_hi:[1,0,1]
	v_pk_fma_f32 v[34:35], v[132:133], v[194:195], v[34:35] op_sel_hi:[1,0,1]
	v_pk_fma_f32 v[36:37], v[134:135], v[194:195], v[36:37] op_sel_hi:[1,0,1]
	v_pk_fma_f32 v[30:31], v[132:133], v[196:197], v[30:31] op_sel_hi:[1,0,1]
	v_pk_fma_f32 v[32:33], v[134:135], v[196:197], v[32:33] op_sel_hi:[1,0,1]
	v_pk_fma_f32 v[26:27], v[132:133], v[198:199], v[26:27] op_sel_hi:[1,0,1]
	v_pk_fma_f32 v[28:29], v[134:135], v[198:199], v[28:29] op_sel_hi:[1,0,1]
	ds_read_b32 v190, v49 offset:224
	ds_read_b32 v192, v49 offset:4320
	ds_read_b32 v194, v49 offset:8416
	ds_read_b32 v196, v49 offset:12512
	ds_read_b32 v198, v49 offset:16608
	s_waitcnt vmcnt(9) lgkmcnt(0)
	v_pk_fma_f32 v[42:43], v[136:137], v[190:191], v[42:43] op_sel_hi:[1,0,1]
	v_pk_fma_f32 v[44:45], v[138:139], v[190:191], v[44:45] op_sel_hi:[1,0,1]
	v_pk_fma_f32 v[38:39], v[136:137], v[192:193], v[38:39] op_sel_hi:[1,0,1]
	v_pk_fma_f32 v[40:41], v[138:139], v[192:193], v[40:41] op_sel_hi:[1,0,1]
	v_pk_fma_f32 v[34:35], v[136:137], v[194:195], v[34:35] op_sel_hi:[1,0,1]
	v_pk_fma_f32 v[36:37], v[138:139], v[194:195], v[36:37] op_sel_hi:[1,0,1]
	v_pk_fma_f32 v[30:31], v[136:137], v[196:197], v[30:31] op_sel_hi:[1,0,1]
	v_pk_fma_f32 v[32:33], v[138:139], v[196:197], v[32:33] op_sel_hi:[1,0,1]
	v_pk_fma_f32 v[26:27], v[136:137], v[198:199], v[26:27] op_sel_hi:[1,0,1]
	v_pk_fma_f32 v[28:29], v[138:139], v[198:199], v[28:29] op_sel_hi:[1,0,1]
	ds_read_b32 v190, v49 offset:336
	ds_read_b32 v192, v49 offset:4432
	ds_read_b32 v194, v49 offset:8528
	ds_read_b32 v196, v49 offset:12624
	ds_read_b32 v198, v49 offset:16720
	s_waitcnt vmcnt(8) lgkmcnt(0)
; __device__ __forceinline__ void prologue(const Args& A, LAS unsigned char* lds, int vcu, int G, const int tid) {
;     ...
; #pragma unroll 8
;                 for (int kk = 0; kk < 37; ++kk) { const int k = kg + 28 * kk; if (k < 1024) { const f32x4 w = __builtin_nontemporal_load((const f32x4*)(wp + (size_t)k * MODLD));
;                     a0 += w * sc[k]; a1 += w * sc[1024 + k]; a2 += w * sc[2048 + k]; a3 += w * sc[3072 + k]; a4 += w * sc[4096 + k]; } }
	v_pk_fma_f32 v[42:43], v[140:141], v[190:191], v[42:43] op_sel_hi:[1,0,1]
	v_pk_fma_f32 v[44:45], v[142:143], v[190:191], v[44:45] op_sel_hi:[1,0,1]
	v_pk_fma_f32 v[38:39], v[140:141], v[192:193], v[38:39] op_sel_hi:[1,0,1]
	v_pk_fma_f32 v[40:41], v[142:143], v[192:193], v[40:41] op_sel_hi:[1,0,1]
	v_pk_fma_f32 v[34:35], v[140:141], v[194:195], v[34:35] op_sel_hi:[1,0,1]
	v_pk_fma_f32 v[36:37], v[142:143], v[194:195], v[36:37] op_sel_hi:[1,0,1]
	v_pk_fma_f32 v[30:31], v[140:141], v[196:197], v[30:31] op_sel_hi:[1,0,1]
	v_pk_fma_f32 v[32:33], v[142:143], v[196:197], v[32:33] op_sel_hi:[1,0,1]
	v_pk_fma_f32 v[26:27], v[140:141], v[198:199], v[26:27] op_sel_hi:[1,0,1]
	v_pk_fma_f32 v[28:29], v[142:143], v[198:199], v[28:29] op_sel_hi:[1,0,1]
	ds_read_b32 v190, v49 offset:448
	ds_read_b32 v192, v49 offset:4544
	ds_read_b32 v194, v49 offset:8640
	ds_read_b32 v196, v49 offset:12736
	ds_read_b32 v198, v49 offset:16832
	s_waitcnt vmcnt(7) lgkmcnt(0)
	v_pk_fma_f32 v[42:43], v[144:145], v[190:191], v[42:43] op_sel_hi:[1,0,1]
	v_pk_fma_f32 v[44:45], v[146:147], v[190:191], v[44:45] op_sel_hi:[1,0,1]
	v_pk_fma_f32 v[38:39], v[144:145], v[192:193], v[38:39] op_sel_hi:[1,0,1]
	v_pk_fma_f32 v[40:41], v[146:147], v[192:193], v[40:41] op_sel_hi:[1,0,1]
	v_pk_fma_f32 v[34:35], v[144:145], v[194:195], v[34:35] op_sel_hi:[1,0,1]
	v_pk_fma_f32 v[36:37], v[146:147], v[194:195], v[36:37] op_sel_hi:[1,0,1]
	v_pk_fma_f32 v[30:31], v[144:145], v[196:197], v[30:31] op_sel_hi:[1,0,1]
	v_pk_fma_f32 v[32:33], v[146:147], v[196:197], v[32:33] op_sel_hi:[1,0,1]
	v_pk_fma_f32 v[26:27], v[144:145], v[198:199], v[26:27] op_sel_hi:[1,0,1]
	v_pk_fma_f32 v[28:29], v[146:147], v[198:199], v[28:29] op_sel_hi:[1,0,1]
	ds_read_b32 v190, v49 offset:560
	ds_read_b32 v192, v49 offset:4656
	ds_read_b32 v194, v49 offset:8752
	ds_read_b32 v196, v49 offset:12848
	ds_read_b32 v198, v49 offset:16944
	s_waitcnt vmcnt(6) lgkmcnt(0)
	v_pk_fma_f32 v[42:43], v[148:149], v[190:191], v[42:43] op_sel_hi:[1,0,1]
	v_pk_fma_f32 v[44:45], v[150:151], v[190:191], v[44:45] op_sel_hi:[1,0,1]
	v_pk_fma_f32 v[38:39], v[148:149], v[192:193], v[38:39] op_sel_hi:[1,0,1]
	v_pk_fma_f32 v[40:41], v[150:151], v[192:193], v[40:41] op_sel_hi:[1,0,1]
	v_pk_fma_f32 v[34:35], v[148:149], v[194:195], v[34:35] op_sel_hi:[1,0,1]
	v_pk_fma_f32 v[36:37], v[150:151], v[194:195], v[36:37] op_sel_hi:[1,0,1]
	v_pk_fma_f32 v[30:31], v[148:149], v[196:197], v[30:31] op_sel_hi:[1,0,1]
	v_pk_fma_f32 v[32:33], v[150:151], v[196:197], v[32:33] op_sel_hi:[1,0,1]
	v_pk_fma_f32 v[26:27], v[148:149], v[198:199], v[26:27] op_sel_hi:[1,0,1]
	v_pk_fma_f32 v[28:29], v[150:151], v[198:199], v[28:29] op_sel_hi:[1,0,1]
	ds_read_b32 v190, v49 offset:672
	ds_read_b32 v192, v49 offset:4768
	ds_read_b32 v194, v49 offset:8864
	ds_read_b32 v196, v49 offset:12960
	ds_read_b32 v198, v49 offset:17056
	s_waitcnt vmcnt(5) lgkmcnt(0)
	v_pk_fma_f32 v[42:43], v[152:153], v[190:191], v[42:43] op_sel_hi:[1,0,1]
	v_pk_fma_f32 v[44:45], v[154:155], v[190:191], v[44:45] op_sel_hi:[1,0,1]
	v_pk_fma_f32 v[38:39], v[152:153], v[192:193], v[38:39] op_sel_hi:[1,0,1]
	v_pk_fma_f32 v[40:41], v[154:155], v[192:193], v[40:41] op_sel_hi:[1,0,1]
	v_pk_fma_f32 v[34:35], v[152:153], v[194:195], v[34:35] op_sel_hi:[1,0,1]
	v_pk_fma_f32 v[36:37], v[154:155], v[194:195], v[36:37] op_sel_hi:[1,0,1]
	v_pk_fma_f32 v[30:31], v[152:153], v[196:197], v[30:31] op_sel_hi:[1,0,1]
	v_pk_fma_f32 v[32:33], v[154:155], v[196:197], v[32:33] op_sel_hi:[1,0,1]
	v_pk_fma_f32 v[26:27], v[152:153], v[198:199], v[26:27] op_sel_hi:[1,0,1]
	v_pk_fma_f32 v[28:29], v[154:155], v[198:199], v[28:29] op_sel_hi:[1,0,1]
	ds_read_b32 v190, v49 offset:784
	ds_read_b32 v192, v49 offset:4880
	ds_read_b32 v194, v49 offset:8976
	ds_read_b32 v196, v49 offset:13072
	ds_read_b32 v198, v49 offset:17168
	s_waitcnt vmcnt(4) lgkmcnt(0)
	v_pk_fma_f32 v[42:43], v[156:157], v[190:191], v[42:43] op_sel_hi:[1,0,1]
	v_pk_fma_f32 v[44:45], v[158:159], v[190:191], v[44:45] op_sel_hi:[1,0,1]
	v_pk_fma_f32 v[38:39], v[156:157], v[192:193], v[38:39] op_sel_hi:[1,0,1]
	v_pk_fma_f32 v[40:41], v[158:159], v[192:193], v[40:41] op_sel_hi:[1,0,1]
	v_pk_fma_f32 v[34:35], v[156:157], v[194:195], v[34:35] op_sel_hi:[1,0,1]
	v_pk_fma_f32 v[36:37], v[158:159], v[194:195], v[36:37] op_sel_hi:[1,0,1]
	v_pk_fma_f32 v[30:31], v[156:157], v[196:197], v[30:31] op_sel_hi:[1,0,1]
	v_pk_fma_f32 v[32:33], v[158:159], v[196:197], v[32:33] op_sel_hi:[1,0,1]
	v_pk_fma_f32 v[26:27], v[156:157], v[198:199], v[26:27] op_sel_hi:[1,0,1]
	v_pk_fma_f32 v[28:29], v[158:159], v[198:199], v[28:29] op_sel_hi:[1,0,1]
	ds_read_b32 v190, v49 offset:896
	ds_read_b32 v192, v49 offset:4992
	ds_read_b32 v194, v49 offset:9088
	ds_read_b32 v196, v49 offset:13184
	ds_read_b32 v198, v49 offset:17280
	s_waitcnt vmcnt(3) lgkmcnt(0)
	v_pk_fma_f32 v[42:43], v[160:161], v[190:191], v[42:43] op_sel_hi:[1,0,1]
	v_pk_fma_f32 v[44:45], v[162:163], v[190:191], v[44:45] op_sel_hi:[1,0,1]
	v_pk_fma_f32 v[38:39], v[160:161], v[192:193], v[38:39] op_sel_hi:[1,0,1]
	v_pk_fma_f32 v[40:41], v[162:163], v[192:193], v[40:41] op_sel_hi:[1,0,1]
	v_pk_fma_f32 v[34:35], v[160:161], v[194:195], v[34:35] op_sel_hi:[1,0,1]
	v_pk_fma_f32 v[36:37], v[162:163], v[194:195], v[36:37] op_sel_hi:[1,0,1]
	v_pk_fma_f32 v[30:31], v[160:161], v[196:197], v[30:31] op_sel_hi:[1,0,1]
	v_pk_fma_f32 v[32:33], v[162:163], v[196:197], v[32:33] op_sel_hi:[1,0,1]
	v_pk_fma_f32 v[26:27], v[160:161], v[198:199], v[26:27] op_sel_hi:[1,0,1]
	v_pk_fma_f32 v[28:29], v[162:163], v[198:199], v[28:29] op_sel_hi:[1,0,1]
	ds_read_b32 v190, v49 offset:1008
	ds_read_b32 v192, v49 offset:5104
	ds_read_b32 v194, v49 offset:9200
	ds_read_b32 v196, v49 offset:13296
	ds_read_b32 v198, v49 offset:17392
	s_waitcnt vmcnt(2) lgkmcnt(0)
; __device__ __forceinline__ void prologue(const Args& A, LAS unsigned char* lds, int vcu, int G, const int tid) {
;     ...
; #pragma unroll 8
;                 for (int kk = 0; kk < 37; ++kk) { const int k = kg + 28 * kk; if (k < 1024) { const f32x4 w = __builtin_nontemporal_load((const f32x4*)(wp + (size_t)k * MODLD));
;                     a0 += w * sc[k]; a1 += w * sc[1024 + k]; a2 += w * sc[2048 + k]; a3 += w * sc[3072 + k]; a4 += w * sc[4096 + k]; } }
	v_pk_fma_f32 v[42:43], v[164:165], v[190:191], v[42:43] op_sel_hi:[1,0,1]
	v_pk_fma_f32 v[44:45], v[166:167], v[190:191], v[44:45] op_sel_hi:[1,0,1]
	v_pk_fma_f32 v[38:39], v[164:165], v[192:193], v[38:39] op_sel_hi:[1,0,1]
	v_pk_fma_f32 v[40:41], v[166:167], v[192:193], v[40:41] op_sel_hi:[1,0,1]
	v_pk_fma_f32 v[34:35], v[164:165], v[194:195], v[34:35] op_sel_hi:[1,0,1]
	v_pk_fma_f32 v[36:37], v[166:167], v[194:195], v[36:37] op_sel_hi:[1,0,1]
	v_pk_fma_f32 v[30:31], v[164:165], v[196:197], v[30:31] op_sel_hi:[1,0,1]
	v_pk_fma_f32 v[32:33], v[166:167], v[196:197], v[32:33] op_sel_hi:[1,0,1]
	v_pk_fma_f32 v[26:27], v[164:165], v[198:199], v[26:27] op_sel_hi:[1,0,1]
	v_pk_fma_f32 v[28:29], v[166:167], v[198:199], v[28:29] op_sel_hi:[1,0,1]
	ds_read_b32 v190, v49 offset:1120
	ds_read_b32 v192, v49 offset:5216
	ds_read_b32 v194, v49 offset:9312
	ds_read_b32 v196, v49 offset:13408
	ds_read_b32 v198, v49 offset:17504
	s_waitcnt vmcnt(1) lgkmcnt(0)
	v_pk_fma_f32 v[42:43], v[168:169], v[190:191], v[42:43] op_sel_hi:[1,0,1]
	v_pk_fma_f32 v[44:45], v[170:171], v[190:191], v[44:45] op_sel_hi:[1,0,1]
	v_pk_fma_f32 v[38:39], v[168:169], v[192:193], v[38:39] op_sel_hi:[1,0,1]
	v_pk_fma_f32 v[40:41], v[170:171], v[192:193], v[40:41] op_sel_hi:[1,0,1]
	v_pk_fma_f32 v[34:35], v[168:169], v[194:195], v[34:35] op_sel_hi:[1,0,1]
	v_pk_fma_f32 v[36:37], v[170:171], v[194:195], v[36:37] op_sel_hi:[1,0,1]
	v_pk_fma_f32 v[30:31], v[168:169], v[196:197], v[30:31] op_sel_hi:[1,0,1]
	v_pk_fma_f32 v[32:33], v[170:171], v[196:197], v[32:33] op_sel_hi:[1,0,1]
	v_pk_fma_f32 v[26:27], v[168:169], v[198:199], v[26:27] op_sel_hi:[1,0,1]
	v_pk_fma_f32 v[28:29], v[170:171], v[198:199], v[28:29] op_sel_hi:[1,0,1]
	ds_read_b32 v190, v49 offset:1232
	ds_read_b32 v192, v49 offset:5328
	ds_read_b32 v194, v49 offset:9424
	ds_read_b32 v196, v49 offset:13520
	ds_read_b32 v198, v49 offset:17616
	s_waitcnt vmcnt(0) lgkmcnt(0)
	v_pk_fma_f32 v[42:43], v[172:173], v[190:191], v[42:43] op_sel_hi:[1,0,1]
	v_pk_fma_f32 v[44:45], v[174:175], v[190:191], v[44:45] op_sel_hi:[1,0,1]
	v_pk_fma_f32 v[38:39], v[172:173], v[192:193], v[38:39] op_sel_hi:[1,0,1]
	v_pk_fma_f32 v[40:41], v[174:175], v[192:193], v[40:41] op_sel_hi:[1,0,1]
	v_pk_fma_f32 v[34:35], v[172:173], v[194:195], v[34:35] op_sel_hi:[1,0,1]
	v_pk_fma_f32 v[36:37], v[174:175], v[194:195], v[36:37] op_sel_hi:[1,0,1]
	v_pk_fma_f32 v[30:31], v[172:173], v[196:197], v[30:31] op_sel_hi:[1,0,1]
	v_pk_fma_f32 v[32:33], v[174:175], v[196:197], v[32:33] op_sel_hi:[1,0,1]
	v_pk_fma_f32 v[26:27], v[172:173], v[198:199], v[26:27] op_sel_hi:[1,0,1]
	v_pk_fma_f32 v[28:29], v[174:175], v[198:199], v[28:29] op_sel_hi:[1,0,1]
	s_mov_b32 s44, 0xbd0000
	v_lshl_add_u64 v[188:189], v[80:81], 0, s[44:45]
	global_load_dwordx4 v[128:131], v[188:189], off nt
	s_mov_b32 s44, 0xccc000
	v_lshl_add_u64 v[188:189], v[80:81], 0, s[44:45]
	global_load_dwordx4 v[132:135], v[188:189], off nt
	s_mov_b32 s44, 0xdc8000
	v_lshl_add_u64 v[188:189], v[80:81], 0, s[44:45]
	global_load_dwordx4 v[136:139], v[188:189], off nt
	s_mov_b32 s44, 0xec4000
	v_lshl_add_u64 v[188:189], v[80:81], 0, s[44:45]
	global_load_dwordx4 v[140:143], v[188:189], off nt
	s_mov_b32 s44, 0xfc0000
	v_lshl_add_u64 v[188:189], v[80:81], 0, s[44:45]
	global_load_dwordx4 v[144:147], v[188:189], off nt
	s_mov_b32 s44, 0x10bc000
	v_lshl_add_u64 v[188:189], v[80:81], 0, s[44:45]
	global_load_dwordx4 v[148:151], v[188:189], off nt
	s_mov_b32 s44, 0x11b8000
	v_lshl_add_u64 v[188:189], v[80:81], 0, s[44:45]
	global_load_dwordx4 v[152:155], v[188:189], off nt
	s_mov_b32 s44, 0x12b4000
	v_lshl_add_u64 v[188:189], v[80:81], 0, s[44:45]
	global_load_dwordx4 v[156:159], v[188:189], off nt
	s_mov_b32 s44, 0x13b0000
	v_lshl_add_u64 v[188:189], v[80:81], 0, s[44:45]
	global_load_dwordx4 v[160:163], v[188:189], off nt
	s_mov_b32 s44, 0x14ac000
	v_lshl_add_u64 v[188:189], v[80:81], 0, s[44:45]
	global_load_dwordx4 v[164:167], v[188:189], off nt
	s_mov_b32 s44, 0x15a8000
	v_lshl_add_u64 v[188:189], v[80:81], 0, s[44:45]
	global_load_dwordx4 v[168:171], v[188:189], off nt
	s_mov_b32 s44, 0x16a4000
	v_lshl_add_u64 v[188:189], v[80:81], 0, s[44:45]
	global_load_dwordx4 v[172:175], v[188:189], off nt
	ds_read_b32 v190, v49 offset:1344
	ds_read_b32 v192, v49 offset:5440
	ds_read_b32 v194, v49 offset:9536
	ds_read_b32 v196, v49 offset:13632
	ds_read_b32 v198, v49 offset:17728
	s_waitcnt vmcnt(11) lgkmcnt(0)
	v_pk_fma_f32 v[42:43], v[128:129], v[190:191], v[42:43] op_sel_hi:[1,0,1]
	v_pk_fma_f32 v[44:45], v[130:131], v[190:191], v[44:45] op_sel_hi:[1,0,1]
	v_pk_fma_f32 v[38:39], v[128:129], v[192:193], v[38:39] op_sel_hi:[1,0,1]
	v_pk_fma_f32 v[40:41], v[130:131], v[192:193], v[40:41] op_sel_hi:[1,0,1]
	v_pk_fma_f32 v[34:35], v[128:129], v[194:195], v[34:35] op_sel_hi:[1,0,1]
	v_pk_fma_f32 v[36:37], v[130:131], v[194:195], v[36:37] op_sel_hi:[1,0,1]
	v_pk_fma_f32 v[30:31], v[128:129], v[196:197], v[30:31] op_sel_hi:[1,0,1]
	v_pk_fma_f32 v[32:33], v[130:131], v[196:197], v[32:33] op_sel_hi:[1,0,1]
	v_pk_fma_f32 v[26:27], v[128:129], v[198:199], v[26:27] op_sel_hi:[1,0,1]
	v_pk_fma_f32 v[28:29], v[130:131], v[198:199], v[28:29] op_sel_hi:[1,0,1]
	ds_read_b32 v190, v49 offset:1456
	ds_read_b32 v192, v49 offset:5552
	ds_read_b32 v194, v49 offset:9648
	ds_read_b32 v196, v49 offset:13744
	ds_read_b32 v198, v49 offset:17840
	s_waitcnt vmcnt(10) lgkmcnt(0)
; __device__ __forceinline__ void prologue(const Args& A, LAS unsigned char* lds, int vcu, int G, const int tid) {
;     ...
; #pragma unroll 8
;                 for (int kk = 0; kk < 37; ++kk) { const int k = kg + 28 * kk; if (k < 1024) { const f32x4 w = __builtin_nontemporal_load((const f32x4*)(wp + (size_t)k * MODLD));
;                     a0 += w * sc[k]; a1 += w * sc[1024 + k]; a2 += w * sc[2048 + k]; a3 += w * sc[3072 + k]; a4 += w * sc[4096 + k]; } }
	v_pk_fma_f32 v[42:43], v[132:133], v[190:191], v[42:43] op_sel_hi:[1,0,1]
	v_pk_fma_f32 v[44:45], v[134:135], v[190:191], v[44:45] op_sel_hi:[1,0,1]
	v_pk_fma_f32 v[38:39], v[132:133], v[192:193], v[38:39] op_sel_hi:[1,0,1]
	v_pk_fma_f32 v[40:41], v[134:135], v[192:193], v[40:41] op_sel_hi:[1,0,1]
	v_pk_fma_f32 v[34:35], v[132:133], v[194:195], v[34:35] op_sel_hi:[1,0,1]
	v_pk_fma_f32 v[36:37], v[134:135], v[194:195], v[36:37] op_sel_hi:[1,0,1]
	v_pk_fma_f32 v[30:31], v[132:133], v[196:197], v[30:31] op_sel_hi:[1,0,1]
	v_pk_fma_f32 v[32:33], v[134:135], v[196:197], v[32:33] op_sel_hi:[1,0,1]
	v_pk_fma_f32 v[26:27], v[132:133], v[198:199], v[26:27] op_sel_hi:[1,0,1]
	v_pk_fma_f32 v[28:29], v[134:135], v[198:199], v[28:29] op_sel_hi:[1,0,1]
	ds_read_b32 v190, v49 offset:1568
	ds_read_b32 v192, v49 offset:5664
	ds_read_b32 v194, v49 offset:9760
	ds_read_b32 v196, v49 offset:13856
	ds_read_b32 v198, v49 offset:17952
	s_waitcnt vmcnt(9) lgkmcnt(0)
	v_pk_fma_f32 v[42:43], v[136:137], v[190:191], v[42:43] op_sel_hi:[1,0,1]
	v_pk_fma_f32 v[44:45], v[138:139], v[190:191], v[44:45] op_sel_hi:[1,0,1]
	v_pk_fma_f32 v[38:39], v[136:137], v[192:193], v[38:39] op_sel_hi:[1,0,1]
	v_pk_fma_f32 v[40:41], v[138:139], v[192:193], v[40:41] op_sel_hi:[1,0,1]
	v_pk_fma_f32 v[34:35], v[136:137], v[194:195], v[34:35] op_sel_hi:[1,0,1]
	v_pk_fma_f32 v[36:37], v[138:139], v[194:195], v[36:37] op_sel_hi:[1,0,1]
	v_pk_fma_f32 v[30:31], v[136:137], v[196:197], v[30:31] op_sel_hi:[1,0,1]
	v_pk_fma_f32 v[32:33], v[138:139], v[196:197], v[32:33] op_sel_hi:[1,0,1]
	v_pk_fma_f32 v[26:27], v[136:137], v[198:199], v[26:27] op_sel_hi:[1,0,1]
	v_pk_fma_f32 v[28:29], v[138:139], v[198:199], v[28:29] op_sel_hi:[1,0,1]
	ds_read_b32 v190, v49 offset:1680
	ds_read_b32 v192, v49 offset:5776
	ds_read_b32 v194, v49 offset:9872
	ds_read_b32 v196, v49 offset:13968
	ds_read_b32 v198, v49 offset:18064
	s_waitcnt vmcnt(8) lgkmcnt(0)
	v_pk_fma_f32 v[42:43], v[140:141], v[190:191], v[42:43] op_sel_hi:[1,0,1]
	v_pk_fma_f32 v[44:45], v[142:143], v[190:191], v[44:45] op_sel_hi:[1,0,1]
	v_pk_fma_f32 v[38:39], v[140:141], v[192:193], v[38:39] op_sel_hi:[1,0,1]
	v_pk_fma_f32 v[40:41], v[142:143], v[192:193], v[40:41] op_sel_hi:[1,0,1]
	v_pk_fma_f32 v[34:35], v[140:141], v[194:195], v[34:35] op_sel_hi:[1,0,1]
	v_pk_fma_f32 v[36:37], v[142:143], v[194:195], v[36:37] op_sel_hi:[1,0,1]
	v_pk_fma_f32 v[30:31], v[140:141], v[196:197], v[30:31] op_sel_hi:[1,0,1]
	v_pk_fma_f32 v[32:33], v[142:143], v[196:197], v[32:33] op_sel_hi:[1,0,1]
	v_pk_fma_f32 v[26:27], v[140:141], v[198:199], v[26:27] op_sel_hi:[1,0,1]
	v_pk_fma_f32 v[28:29], v[142:143], v[198:199], v[28:29] op_sel_hi:[1,0,1]
	ds_read_b32 v190, v49 offset:1792
	ds_read_b32 v192, v49 offset:5888
	ds_read_b32 v194, v49 offset:9984
	ds_read_b32 v196, v49 offset:14080
	ds_read_b32 v198, v49 offset:18176
	s_waitcnt vmcnt(7) lgkmcnt(0)
	v_pk_fma_f32 v[42:43], v[144:145], v[190:191], v[42:43] op_sel_hi:[1,0,1]
	v_pk_fma_f32 v[44:45], v[146:147], v[190:191], v[44:45] op_sel_hi:[1,0,1]
	v_pk_fma_f32 v[38:39], v[144:145], v[192:193], v[38:39] op_sel_hi:[1,0,1]
	v_pk_fma_f32 v[40:41], v[146:147], v[192:193], v[40:41] op_sel_hi:[1,0,1]
	v_pk_fma_f32 v[34:35], v[144:145], v[194:195], v[34:35] op_sel_hi:[1,0,1]
	v_pk_fma_f32 v[36:37], v[146:147], v[194:195], v[36:37] op_sel_hi:[1,0,1]
	v_pk_fma_f32 v[30:31], v[144:145], v[196:197], v[30:31] op_sel_hi:[1,0,1]
	v_pk_fma_f32 v[32:33], v[146:147], v[196:197], v[32:33] op_sel_hi:[1,0,1]
	v_pk_fma_f32 v[26:27], v[144:145], v[198:199], v[26:27] op_sel_hi:[1,0,1]
	v_pk_fma_f32 v[28:29], v[146:147], v[198:199], v[28:29] op_sel_hi:[1,0,1]
	ds_read_b32 v190, v49 offset:1904
	ds_read_b32 v192, v49 offset:6000
	ds_read_b32 v194, v49 offset:10096
	ds_read_b32 v196, v49 offset:14192
	ds_read_b32 v198, v49 offset:18288
	s_waitcnt vmcnt(6) lgkmcnt(0)
	v_pk_fma_f32 v[42:43], v[148:149], v[190:191], v[42:43] op_sel_hi:[1,0,1]
	v_pk_fma_f32 v[44:45], v[150:151], v[190:191], v[44:45] op_sel_hi:[1,0,1]
	v_pk_fma_f32 v[38:39], v[148:149], v[192:193], v[38:39] op_sel_hi:[1,0,1]
	v_pk_fma_f32 v[40:41], v[150:151], v[192:193], v[40:41] op_sel_hi:[1,0,1]
	v_pk_fma_f32 v[34:35], v[148:149], v[194:195], v[34:35] op_sel_hi:[1,0,1]
	v_pk_fma_f32 v[36:37], v[150:151], v[194:195], v[36:37] op_sel_hi:[1,0,1]
	v_pk_fma_f32 v[30:31], v[148:149], v[196:197], v[30:31] op_sel_hi:[1,0,1]
	v_pk_fma_f32 v[32:33], v[150:151], v[196:197], v[32:33] op_sel_hi:[1,0,1]
	v_pk_fma_f32 v[26:27], v[148:149], v[198:199], v[26:27] op_sel_hi:[1,0,1]
	v_pk_fma_f32 v[28:29], v[150:151], v[198:199], v[28:29] op_sel_hi:[1,0,1]
	ds_read_b32 v190, v49 offset:2016
	ds_read_b32 v192, v49 offset:6112
	ds_read_b32 v194, v49 offset:10208
	ds_read_b32 v196, v49 offset:14304
	ds_read_b32 v198, v49 offset:18400
	s_waitcnt vmcnt(5) lgkmcnt(0)
	v_pk_fma_f32 v[42:43], v[152:153], v[190:191], v[42:43] op_sel_hi:[1,0,1]
	v_pk_fma_f32 v[44:45], v[154:155], v[190:191], v[44:45] op_sel_hi:[1,0,1]
	v_pk_fma_f32 v[38:39], v[152:153], v[192:193], v[38:39] op_sel_hi:[1,0,1]
	v_pk_fma_f32 v[40:41], v[154:155], v[192:193], v[40:41] op_sel_hi:[1,0,1]
	v_pk_fma_f32 v[34:35], v[152:153], v[194:195], v[34:35] op_sel_hi:[1,0,1]
	v_pk_fma_f32 v[36:37], v[154:155], v[194:195], v[36:37] op_sel_hi:[1,0,1]
	v_pk_fma_f32 v[30:31], v[152:153], v[196:197], v[30:31] op_sel_hi:[1,0,1]
	v_pk_fma_f32 v[32:33], v[154:155], v[196:197], v[32:33] op_sel_hi:[1,0,1]
	v_pk_fma_f32 v[26:27], v[152:153], v[198:199], v[26:27] op_sel_hi:[1,0,1]
	v_pk_fma_f32 v[28:29], v[154:155], v[198:199], v[28:29] op_sel_hi:[1,0,1]
	ds_read_b32 v190, v49 offset:2128
	ds_read_b32 v192, v49 offset:6224
	ds_read_b32 v194, v49 offset:10320
	ds_read_b32 v196, v49 offset:14416
	ds_read_b32 v198, v49 offset:18512
	s_waitcnt vmcnt(4) lgkmcnt(0)
; __device__ __forceinline__ void prologue(const Args& A, LAS unsigned char* lds, int vcu, int G, const int tid) {
;     ...
; #pragma unroll 8
;                 for (int kk = 0; kk < 37; ++kk) { const int k = kg + 28 * kk; if (k < 1024) { const f32x4 w = __builtin_nontemporal_load((const f32x4*)(wp + (size_t)k * MODLD));
;                     a0 += w * sc[k]; a1 += w * sc[1024 + k]; a2 += w * sc[2048 + k]; a3 += w * sc[3072 + k]; a4 += w * sc[4096 + k]; } }
	v_pk_fma_f32 v[42:43], v[156:157], v[190:191], v[42:43] op_sel_hi:[1,0,1]
	v_pk_fma_f32 v[44:45], v[158:159], v[190:191], v[44:45] op_sel_hi:[1,0,1]
	v_pk_fma_f32 v[38:39], v[156:157], v[192:193], v[38:39] op_sel_hi:[1,0,1]
	v_pk_fma_f32 v[40:41], v[158:159], v[192:193], v[40:41] op_sel_hi:[1,0,1]
	v_pk_fma_f32 v[34:35], v[156:157], v[194:195], v[34:35] op_sel_hi:[1,0,1]
	v_pk_fma_f32 v[36:37], v[158:159], v[194:195], v[36:37] op_sel_hi:[1,0,1]
	v_pk_fma_f32 v[30:31], v[156:157], v[196:197], v[30:31] op_sel_hi:[1,0,1]
	v_pk_fma_f32 v[32:33], v[158:159], v[196:197], v[32:33] op_sel_hi:[1,0,1]
	v_pk_fma_f32 v[26:27], v[156:157], v[198:199], v[26:27] op_sel_hi:[1,0,1]
	v_pk_fma_f32 v[28:29], v[158:159], v[198:199], v[28:29] op_sel_hi:[1,0,1]
	ds_read_b32 v190, v49 offset:2240
	ds_read_b32 v192, v49 offset:6336
	ds_read_b32 v194, v49 offset:10432
	ds_read_b32 v196, v49 offset:14528
	ds_read_b32 v198, v49 offset:18624
	s_waitcnt vmcnt(3) lgkmcnt(0)
	v_pk_fma_f32 v[42:43], v[160:161], v[190:191], v[42:43] op_sel_hi:[1,0,1]
	v_pk_fma_f32 v[44:45], v[162:163], v[190:191], v[44:45] op_sel_hi:[1,0,1]
	v_pk_fma_f32 v[38:39], v[160:161], v[192:193], v[38:39] op_sel_hi:[1,0,1]
	v_pk_fma_f32 v[40:41], v[162:163], v[192:193], v[40:41] op_sel_hi:[1,0,1]
	v_pk_fma_f32 v[34:35], v[160:161], v[194:195], v[34:35] op_sel_hi:[1,0,1]
	v_pk_fma_f32 v[36:37], v[162:163], v[194:195], v[36:37] op_sel_hi:[1,0,1]
	v_pk_fma_f32 v[30:31], v[160:161], v[196:197], v[30:31] op_sel_hi:[1,0,1]
	v_pk_fma_f32 v[32:33], v[162:163], v[196:197], v[32:33] op_sel_hi:[1,0,1]
	v_pk_fma_f32 v[26:27], v[160:161], v[198:199], v[26:27] op_sel_hi:[1,0,1]
	v_pk_fma_f32 v[28:29], v[162:163], v[198:199], v[28:29] op_sel_hi:[1,0,1]
	ds_read_b32 v190, v49 offset:2352
	ds_read_b32 v192, v49 offset:6448
	ds_read_b32 v194, v49 offset:10544
	ds_read_b32 v196, v49 offset:14640
	ds_read_b32 v198, v49 offset:18736
	s_waitcnt vmcnt(2) lgkmcnt(0)
	v_pk_fma_f32 v[42:43], v[164:165], v[190:191], v[42:43] op_sel_hi:[1,0,1]
	v_pk_fma_f32 v[44:45], v[166:167], v[190:191], v[44:45] op_sel_hi:[1,0,1]
	v_pk_fma_f32 v[38:39], v[164:165], v[192:193], v[38:39] op_sel_hi:[1,0,1]
	v_pk_fma_f32 v[40:41], v[166:167], v[192:193], v[40:41] op_sel_hi:[1,0,1]
	v_pk_fma_f32 v[34:35], v[164:165], v[194:195], v[34:35] op_sel_hi:[1,0,1]
	v_pk_fma_f32 v[36:37], v[166:167], v[194:195], v[36:37] op_sel_hi:[1,0,1]
	v_pk_fma_f32 v[30:31], v[164:165], v[196:197], v[30:31] op_sel_hi:[1,0,1]
	v_pk_fma_f32 v[32:33], v[166:167], v[196:197], v[32:33] op_sel_hi:[1,0,1]
	v_pk_fma_f32 v[26:27], v[164:165], v[198:199], v[26:27] op_sel_hi:[1,0,1]
	v_pk_fma_f32 v[28:29], v[166:167], v[198:199], v[28:29] op_sel_hi:[1,0,1]
	ds_read_b32 v190, v49 offset:2464
	ds_read_b32 v192, v49 offset:6560
	ds_read_b32 v194, v49 offset:10656
	ds_read_b32 v196, v49 offset:14752
	ds_read_b32 v198, v49 offset:18848
	s_waitcnt vmcnt(1) lgkmcnt(0)
	v_pk_fma_f32 v[42:43], v[168:169], v[190:191], v[42:43] op_sel_hi:[1,0,1]
	v_pk_fma_f32 v[44:45], v[170:171], v[190:191], v[44:45] op_sel_hi:[1,0,1]
	v_pk_fma_f32 v[38:39], v[168:169], v[192:193], v[38:39] op_sel_hi:[1,0,1]
	v_pk_fma_f32 v[40:41], v[170:171], v[192:193], v[40:41] op_sel_hi:[1,0,1]
	v_pk_fma_f32 v[34:35], v[168:169], v[194:195], v[34:35] op_sel_hi:[1,0,1]
	v_pk_fma_f32 v[36:37], v[170:171], v[194:195], v[36:37] op_sel_hi:[1,0,1]
	v_pk_fma_f32 v[30:31], v[168:169], v[196:197], v[30:31] op_sel_hi:[1,0,1]
	v_pk_fma_f32 v[32:33], v[170:171], v[196:197], v[32:33] op_sel_hi:[1,0,1]
	v_pk_fma_f32 v[26:27], v[168:169], v[198:199], v[26:27] op_sel_hi:[1,0,1]
	v_pk_fma_f32 v[28:29], v[170:171], v[198:199], v[28:29] op_sel_hi:[1,0,1]
	ds_read_b32 v190, v49 offset:2576
	ds_read_b32 v192, v49 offset:6672
	ds_read_b32 v194, v49 offset:10768
	ds_read_b32 v196, v49 offset:14864
	ds_read_b32 v198, v49 offset:18960
	s_waitcnt vmcnt(0) lgkmcnt(0)
	v_pk_fma_f32 v[42:43], v[172:173], v[190:191], v[42:43] op_sel_hi:[1,0,1]
	v_pk_fma_f32 v[44:45], v[174:175], v[190:191], v[44:45] op_sel_hi:[1,0,1]
	v_pk_fma_f32 v[38:39], v[172:173], v[192:193], v[38:39] op_sel_hi:[1,0,1]
	v_pk_fma_f32 v[40:41], v[174:175], v[192:193], v[40:41] op_sel_hi:[1,0,1]
	v_pk_fma_f32 v[34:35], v[172:173], v[194:195], v[34:35] op_sel_hi:[1,0,1]
	v_pk_fma_f32 v[36:37], v[174:175], v[194:195], v[36:37] op_sel_hi:[1,0,1]
	v_pk_fma_f32 v[30:31], v[172:173], v[196:197], v[30:31] op_sel_hi:[1,0,1]
	v_pk_fma_f32 v[32:33], v[174:175], v[196:197], v[32:33] op_sel_hi:[1,0,1]
	v_pk_fma_f32 v[26:27], v[172:173], v[198:199], v[26:27] op_sel_hi:[1,0,1]
	v_pk_fma_f32 v[28:29], v[174:175], v[198:199], v[28:29] op_sel_hi:[1,0,1]
	s_mov_b32 s44, 0x17a0000
	v_lshl_add_u64 v[188:189], v[80:81], 0, s[44:45]
	global_load_dwordx4 v[128:131], v[188:189], off nt
	s_mov_b32 s44, 0x189c000
	v_lshl_add_u64 v[188:189], v[80:81], 0, s[44:45]
	global_load_dwordx4 v[132:135], v[188:189], off nt
	s_mov_b32 s44, 0x1998000
	v_lshl_add_u64 v[188:189], v[80:81], 0, s[44:45]
	global_load_dwordx4 v[136:139], v[188:189], off nt
	s_mov_b32 s44, 0x1a94000
	v_lshl_add_u64 v[188:189], v[80:81], 0, s[44:45]
	global_load_dwordx4 v[140:143], v[188:189], off nt
	s_mov_b32 s44, 0x1b90000
	v_lshl_add_u64 v[188:189], v[80:81], 0, s[44:45]
	global_load_dwordx4 v[144:147], v[188:189], off nt
	s_mov_b32 s44, 0x1c8c000
	v_lshl_add_u64 v[188:189], v[80:81], 0, s[44:45]
	global_load_dwordx4 v[148:151], v[188:189], off nt
	s_mov_b32 s44, 0x1d88000
	v_lshl_add_u64 v[188:189], v[80:81], 0, s[44:45]
	global_load_dwordx4 v[152:155], v[188:189], off nt
	s_mov_b32 s44, 0x1e84000
	v_lshl_add_u64 v[188:189], v[80:81], 0, s[44:45]
	global_load_dwordx4 v[156:159], v[188:189], off nt
	s_mov_b32 s44, 0x1f80000
	v_lshl_add_u64 v[188:189], v[80:81], 0, s[44:45]
	global_load_dwordx4 v[160:163], v[188:189], off nt
	s_mov_b32 s44, 0x207c000
	v_lshl_add_u64 v[188:189], v[80:81], 0, s[44:45]
	global_load_dwordx4 v[164:167], v[188:189], off nt
	s_mov_b32 s44, 0x2178000
	v_lshl_add_u64 v[188:189], v[80:81], 0, s[44:45]
	global_load_dwordx4 v[168:171], v[188:189], off nt
	s_mov_b32 s44, 0x2274000
	v_lshl_add_u64 v[188:189], v[80:81], 0, s[44:45]
	global_load_dwordx4 v[172:175], v[188:189], off nt
	ds_read_b32 v190, v49 offset:2688
	ds_read_b32 v192, v49 offset:6784
	ds_read_b32 v194, v49 offset:10880
	ds_read_b32 v196, v49 offset:14976
	ds_read_b32 v198, v49 offset:19072
	s_waitcnt vmcnt(11) lgkmcnt(0)
; __device__ __forceinline__ void prologue(const Args& A, LAS unsigned char* lds, int vcu, int G, const int tid) {
;     ...
; #pragma unroll 8
;                 for (int kk = 0; kk < 37; ++kk) { const int k = kg + 28 * kk; if (k < 1024) { const f32x4 w = __builtin_nontemporal_load((const f32x4*)(wp + (size_t)k * MODLD));
;                     a0 += w * sc[k]; a1 += w * sc[1024 + k]; a2 += w * sc[2048 + k]; a3 += w * sc[3072 + k]; a4 += w * sc[4096 + k]; } }
	v_pk_fma_f32 v[42:43], v[128:129], v[190:191], v[42:43] op_sel_hi:[1,0,1]
	v_pk_fma_f32 v[44:45], v[130:131], v[190:191], v[44:45] op_sel_hi:[1,0,1]
	v_pk_fma_f32 v[38:39], v[128:129], v[192:193], v[38:39] op_sel_hi:[1,0,1]
	v_pk_fma_f32 v[40:41], v[130:131], v[192:193], v[40:41] op_sel_hi:[1,0,1]
	v_pk_fma_f32 v[34:35], v[128:129], v[194:195], v[34:35] op_sel_hi:[1,0,1]
	v_pk_fma_f32 v[36:37], v[130:131], v[194:195], v[36:37] op_sel_hi:[1,0,1]
	v_pk_fma_f32 v[30:31], v[128:129], v[196:197], v[30:31] op_sel_hi:[1,0,1]
	v_pk_fma_f32 v[32:33], v[130:131], v[196:197], v[32:33] op_sel_hi:[1,0,1]
	v_pk_fma_f32 v[26:27], v[128:129], v[198:199], v[26:27] op_sel_hi:[1,0,1]
	v_pk_fma_f32 v[28:29], v[130:131], v[198:199], v[28:29] op_sel_hi:[1,0,1]
	ds_read_b32 v190, v49 offset:2800
	ds_read_b32 v192, v49 offset:6896
	ds_read_b32 v194, v49 offset:10992
	ds_read_b32 v196, v49 offset:15088
	ds_read_b32 v198, v49 offset:19184
	s_waitcnt vmcnt(10) lgkmcnt(0)
	v_pk_fma_f32 v[42:43], v[132:133], v[190:191], v[42:43] op_sel_hi:[1,0,1]
	v_pk_fma_f32 v[44:45], v[134:135], v[190:191], v[44:45] op_sel_hi:[1,0,1]
	v_pk_fma_f32 v[38:39], v[132:133], v[192:193], v[38:39] op_sel_hi:[1,0,1]
	v_pk_fma_f32 v[40:41], v[134:135], v[192:193], v[40:41] op_sel_hi:[1,0,1]
	v_pk_fma_f32 v[34:35], v[132:133], v[194:195], v[34:35] op_sel_hi:[1,0,1]
	v_pk_fma_f32 v[36:37], v[134:135], v[194:195], v[36:37] op_sel_hi:[1,0,1]
	v_pk_fma_f32 v[30:31], v[132:133], v[196:197], v[30:31] op_sel_hi:[1,0,1]
	v_pk_fma_f32 v[32:33], v[134:135], v[196:197], v[32:33] op_sel_hi:[1,0,1]
	v_pk_fma_f32 v[26:27], v[132:133], v[198:199], v[26:27] op_sel_hi:[1,0,1]
	v_pk_fma_f32 v[28:29], v[134:135], v[198:199], v[28:29] op_sel_hi:[1,0,1]
	ds_read_b32 v190, v49 offset:2912
	ds_read_b32 v192, v49 offset:7008
	ds_read_b32 v194, v49 offset:11104
	ds_read_b32 v196, v49 offset:15200
	ds_read_b32 v198, v49 offset:19296
	s_waitcnt vmcnt(9) lgkmcnt(0)
	v_pk_fma_f32 v[42:43], v[136:137], v[190:191], v[42:43] op_sel_hi:[1,0,1]
	v_pk_fma_f32 v[44:45], v[138:139], v[190:191], v[44:45] op_sel_hi:[1,0,1]
	v_pk_fma_f32 v[38:39], v[136:137], v[192:193], v[38:39] op_sel_hi:[1,0,1]
	v_pk_fma_f32 v[40:41], v[138:139], v[192:193], v[40:41] op_sel_hi:[1,0,1]
	v_pk_fma_f32 v[34:35], v[136:137], v[194:195], v[34:35] op_sel_hi:[1,0,1]
	v_pk_fma_f32 v[36:37], v[138:139], v[194:195], v[36:37] op_sel_hi:[1,0,1]
	v_pk_fma_f32 v[30:31], v[136:137], v[196:197], v[30:31] op_sel_hi:[1,0,1]
	v_pk_fma_f32 v[32:33], v[138:139], v[196:197], v[32:33] op_sel_hi:[1,0,1]
	v_pk_fma_f32 v[26:27], v[136:137], v[198:199], v[26:27] op_sel_hi:[1,0,1]
	v_pk_fma_f32 v[28:29], v[138:139], v[198:199], v[28:29] op_sel_hi:[1,0,1]
	ds_read_b32 v190, v49 offset:3024
	ds_read_b32 v192, v49 offset:7120
	ds_read_b32 v194, v49 offset:11216
	ds_read_b32 v196, v49 offset:15312
	ds_read_b32 v198, v49 offset:19408
	s_waitcnt vmcnt(8) lgkmcnt(0)
	v_pk_fma_f32 v[42:43], v[140:141], v[190:191], v[42:43] op_sel_hi:[1,0,1]
	v_pk_fma_f32 v[44:45], v[142:143], v[190:191], v[44:45] op_sel_hi:[1,0,1]
	v_pk_fma_f32 v[38:39], v[140:141], v[192:193], v[38:39] op_sel_hi:[1,0,1]
	v_pk_fma_f32 v[40:41], v[142:143], v[192:193], v[40:41] op_sel_hi:[1,0,1]
	v_pk_fma_f32 v[34:35], v[140:141], v[194:195], v[34:35] op_sel_hi:[1,0,1]
	v_pk_fma_f32 v[36:37], v[142:143], v[194:195], v[36:37] op_sel_hi:[1,0,1]
	v_pk_fma_f32 v[30:31], v[140:141], v[196:197], v[30:31] op_sel_hi:[1,0,1]
	v_pk_fma_f32 v[32:33], v[142:143], v[196:197], v[32:33] op_sel_hi:[1,0,1]
	v_pk_fma_f32 v[26:27], v[140:141], v[198:199], v[26:27] op_sel_hi:[1,0,1]
	v_pk_fma_f32 v[28:29], v[142:143], v[198:199], v[28:29] op_sel_hi:[1,0,1]
	ds_read_b32 v190, v49 offset:3136
	ds_read_b32 v192, v49 offset:7232
	ds_read_b32 v194, v49 offset:11328
	ds_read_b32 v196, v49 offset:15424
	ds_read_b32 v198, v49 offset:19520
	s_waitcnt vmcnt(7) lgkmcnt(0)
	v_pk_fma_f32 v[42:43], v[144:145], v[190:191], v[42:43] op_sel_hi:[1,0,1]
	v_pk_fma_f32 v[44:45], v[146:147], v[190:191], v[44:45] op_sel_hi:[1,0,1]
	v_pk_fma_f32 v[38:39], v[144:145], v[192:193], v[38:39] op_sel_hi:[1,0,1]
	v_pk_fma_f32 v[40:41], v[146:147], v[192:193], v[40:41] op_sel_hi:[1,0,1]
	v_pk_fma_f32 v[34:35], v[144:145], v[194:195], v[34:35] op_sel_hi:[1,0,1]
	v_pk_fma_f32 v[36:37], v[146:147], v[194:195], v[36:37] op_sel_hi:[1,0,1]
	v_pk_fma_f32 v[30:31], v[144:145], v[196:197], v[30:31] op_sel_hi:[1,0,1]
	v_pk_fma_f32 v[32:33], v[146:147], v[196:197], v[32:33] op_sel_hi:[1,0,1]
	v_pk_fma_f32 v[26:27], v[144:145], v[198:199], v[26:27] op_sel_hi:[1,0,1]
	v_pk_fma_f32 v[28:29], v[146:147], v[198:199], v[28:29] op_sel_hi:[1,0,1]
	ds_read_b32 v190, v49 offset:3248
	ds_read_b32 v192, v49 offset:7344
	ds_read_b32 v194, v49 offset:11440
	ds_read_b32 v196, v49 offset:15536
	ds_read_b32 v198, v49 offset:19632
	s_waitcnt vmcnt(6) lgkmcnt(0)
	v_pk_fma_f32 v[42:43], v[148:149], v[190:191], v[42:43] op_sel_hi:[1,0,1]
	v_pk_fma_f32 v[44:45], v[150:151], v[190:191], v[44:45] op_sel_hi:[1,0,1]
	v_pk_fma_f32 v[38:39], v[148:149], v[192:193], v[38:39] op_sel_hi:[1,0,1]
	v_pk_fma_f32 v[40:41], v[150:151], v[192:193], v[40:41] op_sel_hi:[1,0,1]
	v_pk_fma_f32 v[34:35], v[148:149], v[194:195], v[34:35] op_sel_hi:[1,0,1]
	v_pk_fma_f32 v[36:37], v[150:151], v[194:195], v[36:37] op_sel_hi:[1,0,1]
	v_pk_fma_f32 v[30:31], v[148:149], v[196:197], v[30:31] op_sel_hi:[1,0,1]
	v_pk_fma_f32 v[32:33], v[150:151], v[196:197], v[32:33] op_sel_hi:[1,0,1]
	v_pk_fma_f32 v[26:27], v[148:149], v[198:199], v[26:27] op_sel_hi:[1,0,1]
	v_pk_fma_f32 v[28:29], v[150:151], v[198:199], v[28:29] op_sel_hi:[1,0,1]
	ds_read_b32 v190, v49 offset:3360
	ds_read_b32 v192, v49 offset:7456
	ds_read_b32 v194, v49 offset:11552
	ds_read_b32 v196, v49 offset:15648
	ds_read_b32 v198, v49 offset:19744
	s_waitcnt vmcnt(5) lgkmcnt(0)
; #define LAS __attribute__((address_space(3)))
; __device__ __forceinline__ void prologue(const Args& A, LAS unsigned char* lds, int vcu, int G, const int tid) {
;     ...
;             if (kg < 28) {
;                 const float* wp = A.in[I_WADA] + n0 + 4 * c4;
; #pragma unroll 8
;                 for (int kk = 0; kk < 37; ++kk) { const int k = kg + 28 * kk; if (k < 1024) { const f32x4 w = __builtin_nontemporal_load((const f32x4*)(wp + (size_t)k * MODLD));
;                     a0 += w * sc[k]; a1 += w * sc[1024 + k]; a2 += w * sc[2048 + k]; a3 += w * sc[3072 + k]; a4 += w * sc[4096 + k]; } }
;                 *(LAS f32x4*)(red + (0 * 28 + kg) * 72 + 4 * c4) = a0; *(LAS f32x4*)(red + (1 * 28 + kg) * 72 + 4 * c4) = a1; *(LAS f32x4*)(red + (2 * 28 + kg) * 72 + 4 * c4) = a2;
;                 *(LAS f32x4*)(red + (3 * 28 + kg) * 72 + 4 * c4) = a3; *(LAS f32x4*)(red + (4 * 28 + kg) * 72 + 4 * c4) = a4; }
	v_pk_fma_f32 v[42:43], v[152:153], v[190:191], v[42:43] op_sel_hi:[1,0,1]
	v_pk_fma_f32 v[44:45], v[154:155], v[190:191], v[44:45] op_sel_hi:[1,0,1]
	v_pk_fma_f32 v[38:39], v[152:153], v[192:193], v[38:39] op_sel_hi:[1,0,1]
	v_pk_fma_f32 v[40:41], v[154:155], v[192:193], v[40:41] op_sel_hi:[1,0,1]
	v_pk_fma_f32 v[34:35], v[152:153], v[194:195], v[34:35] op_sel_hi:[1,0,1]
	v_pk_fma_f32 v[36:37], v[154:155], v[194:195], v[36:37] op_sel_hi:[1,0,1]
	v_pk_fma_f32 v[30:31], v[152:153], v[196:197], v[30:31] op_sel_hi:[1,0,1]
	v_pk_fma_f32 v[32:33], v[154:155], v[196:197], v[32:33] op_sel_hi:[1,0,1]
	v_pk_fma_f32 v[26:27], v[152:153], v[198:199], v[26:27] op_sel_hi:[1,0,1]
	v_pk_fma_f32 v[28:29], v[154:155], v[198:199], v[28:29] op_sel_hi:[1,0,1]
	ds_read_b32 v190, v49 offset:3472
	ds_read_b32 v192, v49 offset:7568
	ds_read_b32 v194, v49 offset:11664
	ds_read_b32 v196, v49 offset:15760
	ds_read_b32 v198, v49 offset:19856
	s_waitcnt vmcnt(4) lgkmcnt(0)
	v_pk_fma_f32 v[42:43], v[156:157], v[190:191], v[42:43] op_sel_hi:[1,0,1]
	v_pk_fma_f32 v[44:45], v[158:159], v[190:191], v[44:45] op_sel_hi:[1,0,1]
	v_pk_fma_f32 v[38:39], v[156:157], v[192:193], v[38:39] op_sel_hi:[1,0,1]
	v_pk_fma_f32 v[40:41], v[158:159], v[192:193], v[40:41] op_sel_hi:[1,0,1]
	v_pk_fma_f32 v[34:35], v[156:157], v[194:195], v[34:35] op_sel_hi:[1,0,1]
	v_pk_fma_f32 v[36:37], v[158:159], v[194:195], v[36:37] op_sel_hi:[1,0,1]
	v_pk_fma_f32 v[30:31], v[156:157], v[196:197], v[30:31] op_sel_hi:[1,0,1]
	v_pk_fma_f32 v[32:33], v[158:159], v[196:197], v[32:33] op_sel_hi:[1,0,1]
	v_pk_fma_f32 v[26:27], v[156:157], v[198:199], v[26:27] op_sel_hi:[1,0,1]
	v_pk_fma_f32 v[28:29], v[158:159], v[198:199], v[28:29] op_sel_hi:[1,0,1]
	ds_read_b32 v190, v49 offset:3584
	ds_read_b32 v192, v49 offset:7680
	ds_read_b32 v194, v49 offset:11776
	ds_read_b32 v196, v49 offset:15872
	ds_read_b32 v198, v49 offset:19968
	s_waitcnt vmcnt(3) lgkmcnt(0)
	v_pk_fma_f32 v[42:43], v[160:161], v[190:191], v[42:43] op_sel_hi:[1,0,1]
	v_pk_fma_f32 v[44:45], v[162:163], v[190:191], v[44:45] op_sel_hi:[1,0,1]
	v_pk_fma_f32 v[38:39], v[160:161], v[192:193], v[38:39] op_sel_hi:[1,0,1]
	v_pk_fma_f32 v[40:41], v[162:163], v[192:193], v[40:41] op_sel_hi:[1,0,1]
	v_pk_fma_f32 v[34:35], v[160:161], v[194:195], v[34:35] op_sel_hi:[1,0,1]
	v_pk_fma_f32 v[36:37], v[162:163], v[194:195], v[36:37] op_sel_hi:[1,0,1]
	v_pk_fma_f32 v[30:31], v[160:161], v[196:197], v[30:31] op_sel_hi:[1,0,1]
	v_pk_fma_f32 v[32:33], v[162:163], v[196:197], v[32:33] op_sel_hi:[1,0,1]
	v_pk_fma_f32 v[26:27], v[160:161], v[198:199], v[26:27] op_sel_hi:[1,0,1]
	v_pk_fma_f32 v[28:29], v[162:163], v[198:199], v[28:29] op_sel_hi:[1,0,1]
	ds_read_b32 v190, v49 offset:3696
	ds_read_b32 v192, v49 offset:7792
	ds_read_b32 v194, v49 offset:11888
	ds_read_b32 v196, v49 offset:15984
	ds_read_b32 v198, v49 offset:20080
	s_waitcnt vmcnt(2) lgkmcnt(0)
	v_pk_fma_f32 v[42:43], v[164:165], v[190:191], v[42:43] op_sel_hi:[1,0,1]
	v_pk_fma_f32 v[44:45], v[166:167], v[190:191], v[44:45] op_sel_hi:[1,0,1]
	v_pk_fma_f32 v[38:39], v[164:165], v[192:193], v[38:39] op_sel_hi:[1,0,1]
	v_pk_fma_f32 v[40:41], v[166:167], v[192:193], v[40:41] op_sel_hi:[1,0,1]
	v_pk_fma_f32 v[34:35], v[164:165], v[194:195], v[34:35] op_sel_hi:[1,0,1]
	v_pk_fma_f32 v[36:37], v[166:167], v[194:195], v[36:37] op_sel_hi:[1,0,1]
	v_pk_fma_f32 v[30:31], v[164:165], v[196:197], v[30:31] op_sel_hi:[1,0,1]
	v_pk_fma_f32 v[32:33], v[166:167], v[196:197], v[32:33] op_sel_hi:[1,0,1]
	v_pk_fma_f32 v[26:27], v[164:165], v[198:199], v[26:27] op_sel_hi:[1,0,1]
	v_pk_fma_f32 v[28:29], v[166:167], v[198:199], v[28:29] op_sel_hi:[1,0,1]
	ds_read_b32 v190, v49 offset:3808
	ds_read_b32 v192, v49 offset:7904
	ds_read_b32 v194, v49 offset:12000
	ds_read_b32 v196, v49 offset:16096
	ds_read_b32 v198, v49 offset:20192
	s_waitcnt vmcnt(1) lgkmcnt(0)
	v_pk_fma_f32 v[42:43], v[168:169], v[190:191], v[42:43] op_sel_hi:[1,0,1]
	v_pk_fma_f32 v[44:45], v[170:171], v[190:191], v[44:45] op_sel_hi:[1,0,1]
	v_pk_fma_f32 v[38:39], v[168:169], v[192:193], v[38:39] op_sel_hi:[1,0,1]
	v_pk_fma_f32 v[40:41], v[170:171], v[192:193], v[40:41] op_sel_hi:[1,0,1]
	v_pk_fma_f32 v[34:35], v[168:169], v[194:195], v[34:35] op_sel_hi:[1,0,1]
	v_pk_fma_f32 v[36:37], v[170:171], v[194:195], v[36:37] op_sel_hi:[1,0,1]
	v_pk_fma_f32 v[30:31], v[168:169], v[196:197], v[30:31] op_sel_hi:[1,0,1]
	v_pk_fma_f32 v[32:33], v[170:171], v[196:197], v[32:33] op_sel_hi:[1,0,1]
	v_pk_fma_f32 v[26:27], v[168:169], v[198:199], v[26:27] op_sel_hi:[1,0,1]
	v_pk_fma_f32 v[28:29], v[170:171], v[198:199], v[28:29] op_sel_hi:[1,0,1]
	ds_read_b32 v190, v49 offset:3920
	ds_read_b32 v192, v49 offset:8016
	ds_read_b32 v194, v49 offset:12112
	ds_read_b32 v196, v49 offset:16208
	ds_read_b32 v198, v49 offset:20304
	s_waitcnt vmcnt(0) lgkmcnt(0)
	v_pk_fma_f32 v[42:43], v[172:173], v[190:191], v[42:43] op_sel_hi:[1,0,1]
	v_pk_fma_f32 v[44:45], v[174:175], v[190:191], v[44:45] op_sel_hi:[1,0,1]
	v_pk_fma_f32 v[38:39], v[172:173], v[192:193], v[38:39] op_sel_hi:[1,0,1]
	v_pk_fma_f32 v[40:41], v[174:175], v[192:193], v[40:41] op_sel_hi:[1,0,1]
	v_pk_fma_f32 v[34:35], v[172:173], v[194:195], v[34:35] op_sel_hi:[1,0,1]
	v_pk_fma_f32 v[36:37], v[174:175], v[194:195], v[36:37] op_sel_hi:[1,0,1]
	v_pk_fma_f32 v[30:31], v[172:173], v[196:197], v[30:31] op_sel_hi:[1,0,1]
	v_pk_fma_f32 v[32:33], v[174:175], v[196:197], v[32:33] op_sel_hi:[1,0,1]
	v_pk_fma_f32 v[26:27], v[172:173], v[198:199], v[26:27] op_sel_hi:[1,0,1]
	v_pk_fma_f32 v[28:29], v[174:175], v[198:199], v[28:29] op_sel_hi:[1,0,1]
	v_cmp_gt_i32_e32 vcc, 0xd4, v105
	s_and_saveexec_b64 s[46:47], vcc
	s_cbranch_execz .Lgemv_tail_done
	s_mov_b32 s44, 0x2370000
	v_lshl_add_u64 v[188:189], v[80:81], 0, s[44:45]
	global_load_dwordx4 v[128:131], v[188:189], off nt
	ds_read_b32 v190, v49 offset:4032
	ds_read_b32 v192, v49 offset:8128
	ds_read_b32 v194, v49 offset:12224
	ds_read_b32 v196, v49 offset:16320
	ds_read_b32 v198, v49 offset:20416
	s_waitcnt vmcnt(0) lgkmcnt(0)
	v_pk_fma_f32 v[42:43], v[128:129], v[190:191], v[42:43] op_sel_hi:[1,0,1]
	v_pk_fma_f32 v[44:45], v[130:131], v[190:191], v[44:45] op_sel_hi:[1,0,1]
	v_pk_fma_f32 v[38:39], v[128:129], v[192:193], v[38:39] op_sel_hi:[1,0,1]
	v_pk_fma_f32 v[40:41], v[130:131], v[192:193], v[40:41] op_sel_hi:[1,0,1]
	v_pk_fma_f32 v[34:35], v[128:129], v[194:195], v[34:35] op_sel_hi:[1,0,1]
	v_pk_fma_f32 v[36:37], v[130:131], v[194:195], v[36:37] op_sel_hi:[1,0,1]
	v_pk_fma_f32 v[30:31], v[128:129], v[196:197], v[30:31] op_sel_hi:[1,0,1]
	v_pk_fma_f32 v[32:33], v[130:131], v[196:197], v[32:33] op_sel_hi:[1,0,1]
	v_pk_fma_f32 v[26:27], v[128:129], v[198:199], v[26:27] op_sel_hi:[1,0,1]
	v_pk_fma_f32 v[28:29], v[130:131], v[198:199], v[28:29] op_sel_hi:[1,0,1]
.Lgemv_tail_done:
	s_or_b64 exec, exec, s[46:47]
.LBB0_176:
	ds_write_b128 v88, v[42:45] offset:20480
	ds_write_b128 v88, v[38:41] offset:28544
	ds_write_b128 v88, v[34:37] offset:36608
	ds_write_b128 v88, v[30:33] offset:44672
	ds_write_b128 v88, v[26:29] offset:52736
